# k5 plus: negm copy (8 v_mov_b64 per tile pair) removed from MLA loop common path; second half reads C-init from v48..63
# baseline (speedup 1.0000x reference)
.LBB0_265:
	v_mfma_f32_32x32x16_bf16 v[0:15], v[32:35], v[68:71], v[0:15]
	v_mfma_f32_32x32x16_bf16 v[0:15], v[44:47], v[72:75], v[0:15]
	v_mfma_f32_32x32x16_bf16 v[0:15], v[40:43], v[76:79], v[0:15]
	s_waitcnt lgkmcnt(0)
	v_mfma_f32_32x32x16_bf16 v[16:31], v[36:39], v[224:227], v[16:31]
	v_max_f32_e32 v76, v97, v97
	v_max_f32_e32 v77, v96, v96
	v_max_f32_e32 v76, v77, v76
	v_max3_f32 v76, v76, v98, v99
	v_max3_f32 v36, v76, v100, v101
	v_max3_f32 v36, v36, v102, v103
	v_max3_f32 v36, v36, v104, v105
	v_mfma_f32_32x32x16_bf16 v[16:31], v[32:35], v[228:231], v[16:31]
	v_max3_f32 v36, v36, v106, v107
	v_max3_f32 v36, v36, v108, v109
	v_max3_f32 v36, v36, v110, v111
	v_max3_f32 v36, v36, v80, v81
	v_max3_f32 v32, v36, v82, v83
	v_max3_f32 v32, v32, v84, v85
	v_max3_f32 v32, v32, v86, v87
	v_mfma_f32_32x32x16_bf16 v[16:31], v[44:47], v[232:235], v[16:31]
	v_max3_f32 v32, v32, v88, v89
	v_max3_f32 v32, v32, v90, v91
	v_max3_f32 v32, v32, v92, v93
	v_max3_f32 v32, v32, v94, v95
	v_mov_b32_e32 v33, v32
	s_nop 1
	v_permlane32_swap_b32_e32 v32, v33
	v_mfma_f32_32x32x16_bf16 v[16:31], v[40:43], v[236:239], v[16:31]
	v_max_f32_e32 v33, v33, v33
	v_max_f32_e32 v32, v32, v32
	v_max_f32_e32 v32, v32, v33
	v_cmp_ge_f32_e32 vcc, s25, v32
	s_cmp_eq_u64 vcc, exec
	s_cbranch_scc0 .LBB0_279
	v_mov_b32_e32 v181, 1.0
	v_cmp_gt_f32_e32 vcc, 1.0, v181
	s_cbranch_vccz .LBB0_270

.LBB0_270:
	v_exp_f32_e32 v218, v96
	v_exp_f32_e32 v219, v97
	v_exp_f32_e32 v220, v98
	v_exp_f32_e32 v221, v99
	v_exp_f32_e32 v222, v100
	v_exp_f32_e32 v223, v101
	v_exp_f32_e32 v224, v102
	v_exp_f32_e32 v225, v103
	v_exp_f32_e32 v226, v104
	v_exp_f32_e32 v227, v105
	v_exp_f32_e32 v228, v106
	v_exp_f32_e32 v229, v107
	v_exp_f32_e32 v230, v108
	v_exp_f32_e32 v231, v109
	v_exp_f32_e32 v232, v110
	v_exp_f32_e32 v233, v111
	s_waitcnt lgkmcnt(0)
	s_barrier
	v_add_u32_e32 v68, s33, v198
	ds_read_b128 v[64:67], v68 offset:24576
	ds_read_b128 v[210:213], v68 offset:32768
	v_add_u32_e32 v183, s33, v199
	v_exp_f32_e32 v87, v87
	v_exp_f32_e32 v88, v88
	s_waitcnt lgkmcnt(1)
	v_mfma_f32_32x32x16_bf16 v[96:111], v[64:67], v[116:119], v[48:63]
	v_exp_f32_e32 v89, v89
	v_exp_f32_e32 v90, v90
	v_exp_f32_e32 v91, v91
	v_exp_f32_e32 v234, v92
	v_exp_f32_e32 v235, v93
	v_exp_f32_e32 v236, v94
	v_exp_f32_e32 v237, v95
	s_waitcnt lgkmcnt(0)
	v_mfma_f32_32x32x16_bf16 v[64:79], v[210:213], v[116:119], v[48:63]
	ds_read_b128 v[210:213], v183 offset:24576
	ds_read_b128 v[214:217], v183 offset:32768
	v_add_u32_e32 v183, s33, v200
	v_cvt_pk_bf16_f32 v92, v218, v219
	v_cvt_pk_bf16_f32 v93, v220, v221
	v_cvt_pk_bf16_f32 v94, v222, v223
	v_cvt_pk_bf16_f32 v95, v224, v225
	s_waitcnt lgkmcnt(1)
	v_mfma_f32_32x32x16_bf16 v[96:111], v[210:213], v[112:115], v[96:111]
	v_permlane32_swap_b32_e32 v92, v94
	v_permlane32_swap_b32_e32 v93, v95
	s_waitcnt lgkmcnt(0)
	v_mfma_f32_32x32x16_bf16 v[64:79], v[214:217], v[112:115], v[64:79]
	ds_read_b128 v[210:213], v183 offset:24576
	ds_read_b128 v[214:217], v183 offset:32768
	v_add_u32_e32 v183, s33, v201
	s_waitcnt lgkmcnt(1)
	v_mfma_f32_32x32x16_bf16 v[96:111], v[210:213], v[124:127], v[96:111]
	s_waitcnt lgkmcnt(0)
	v_mfma_f32_32x32x16_bf16 v[64:79], v[214:217], v[124:127], v[64:79]
	ds_read_b128 v[210:213], v183 offset:24576
	ds_read_b128 v[214:217], v183 offset:32768
	v_add_u32_e32 v183, s33, v202
	s_waitcnt lgkmcnt(1)
	v_mfma_f32_32x32x16_bf16 v[96:111], v[210:213], v[120:123], v[96:111]
	s_waitcnt lgkmcnt(0)
	v_mfma_f32_32x32x16_bf16 v[64:79], v[214:217], v[120:123], v[64:79]
	ds_read_b128 v[210:213], v183 offset:24576
	ds_read_b128 v[214:217], v183 offset:32768
	v_add_u32_e32 v183, s33, v203
	s_waitcnt lgkmcnt(1)
	v_mfma_f32_32x32x16_bf16 v[96:111], v[210:213], v[132:135], v[96:111]
	s_waitcnt lgkmcnt(0)
	v_mfma_f32_32x32x16_bf16 v[64:79], v[214:217], v[132:135], v[64:79]
	ds_read_b128 v[210:213], v183 offset:24576
	ds_read_b128 v[214:217], v183 offset:32768
	s_waitcnt lgkmcnt(1)
	v_mfma_f32_32x32x16_bf16 v[96:111], v[210:213], v[128:131], v[96:111]
	v_exp_f32_e32 v211, v80
	v_add_f32_e32 v80, 0, v218
	v_add_f32_e32 v80, v219, v80
	v_add_f32_e32 v80, v220, v80
	v_add_f32_e32 v80, v221, v80
	v_add_f32_e32 v80, v222, v80
	v_add_f32_e32 v80, v223, v80
	v_add_f32_e32 v80, v224, v80
	v_add_f32_e32 v80, v225, v80
	v_add_f32_e32 v80, v226, v80
	v_add_f32_e32 v80, v227, v80
	v_add_f32_e32 v80, v228, v80
	v_add_f32_e32 v80, v229, v80
	v_add_f32_e32 v80, v230, v80
	v_exp_f32_e32 v212, v81
	v_add_f32_e32 v80, v231, v80
	v_exp_f32_e32 v213, v82
	v_add_f32_e32 v80, v232, v80
	s_waitcnt lgkmcnt(0)
	v_mfma_f32_32x32x16_bf16 v[64:79], v[214:217], v[128:131], v[64:79]
	v_exp_f32_e32 v214, v83
	v_add_f32_e32 v80, v233, v80
	v_exp_f32_e32 v215, v84
	v_add_f32_e32 v80, v211, v80
	v_exp_f32_e32 v216, v85
	v_add_f32_e32 v80, v212, v80
	v_exp_f32_e32 v217, v86
	v_add_f32_e32 v80, v213, v80
	v_add_f32_e32 v80, v214, v80
	v_add_f32_e32 v80, v215, v80
	v_add_f32_e32 v80, v216, v80
	v_add_f32_e32 v80, v217, v80
	v_add_f32_e32 v80, v87, v80
	v_add_f32_e32 v80, v88, v80
	v_add_f32_e32 v80, v89, v80
	v_add_f32_e32 v80, v90, v80
	v_add_f32_e32 v80, v91, v80
	v_add_f32_e32 v80, v234, v80
	v_add_f32_e32 v80, v235, v80
	v_add_f32_e32 v80, v236, v80
	v_add_f32_e32 v183, v237, v80
	v_mov_b32_e32 v210, v183
	v_cvt_pk_bf16_f32 v80, v226, v227
	v_cvt_pk_bf16_f32 v81, v228, v229
	v_cvt_pk_bf16_f32 v82, v230, v231
	v_cvt_pk_bf16_f32 v83, v232, v233
	v_cvt_pk_bf16_f32 v84, v211, v212
	v_cvt_pk_bf16_f32 v85, v213, v214
	v_cvt_pk_bf16_f32 v86, v215, v216
	v_cvt_pk_bf16_f32 v87, v217, v87
	v_cvt_pk_bf16_f32 v88, v88, v89
	v_cvt_pk_bf16_f32 v89, v90, v91
	v_cvt_pk_bf16_f32 v90, v234, v235
	v_cvt_pk_bf16_f32 v91, v236, v237
	v_lshl_add_u32 v211, s29, 13, v195
	ds_read_b64_tr_b16 v[212:213], v211 offset:0
	ds_read_b64_tr_b16 v[214:215], v211 offset:0x400
	ds_read_b64_tr_b16 v[216:217], v211 offset:0x800
	ds_read_b64_tr_b16 v[218:219], v211 offset:0xc00
	ds_read_b64_tr_b16 v[220:221], v211 offset:0x1000
	ds_read_b64_tr_b16 v[222:223], v211 offset:0x1400
	ds_read_b64_tr_b16 v[224:225], v211 offset:0x1800
	ds_read_b64_tr_b16 v[226:227], v211 offset:0x1c00
	s_nop 1
	v_permlane32_swap_b32_e32 v183, v210
	v_permlane32_swap_b32_e32 v80, v82
	v_permlane32_swap_b32_e32 v81, v83
	v_permlane32_swap_b32_e32 v84, v86
	v_permlane32_swap_b32_e32 v85, v87
	v_permlane32_swap_b32_e32 v88, v90
	v_permlane32_swap_b32_e32 v89, v91
	ds_read_b64_tr_b16 v[228:229], v211 offset:0x200
	ds_read_b64_tr_b16 v[230:231], v211 offset:0x600
	ds_read_b64_tr_b16 v[232:233], v211 offset:0xa00
	ds_read_b64_tr_b16 v[234:235], v211 offset:0xe00
	ds_read_b64_tr_b16 v[236:237], v211 offset:0x1200
	ds_read_b64_tr_b16 v[238:239], v211 offset:0x1600
	ds_read_b64_tr_b16 v[240:241], v211 offset:0x1a00
	s_waitcnt lgkmcnt(7)
	s_nop 0
	v_mfma_f32_32x32x16_bf16 v[0:15], v[92:95], v[212:215], v[0:15]
	ds_read_b64_tr_b16 v[242:243], v211 offset:0x1e00
	v_add_u32_e32 v245, s31, v196
	s_lshl_b32 s31, s28, 14
	s_add_i32 s31, s31, 0
	s_add_i32 s2, s2, 2
	s_cmp_ge_u32 s2, s27
	s_waitcnt vmcnt(2)
	ds_write_b128 v245, v[136:139]
	v_add_u32_e32 v245, s31, v193
	s_cselect_b64 s[52:53], -1, 0
	s_waitcnt vmcnt(1)
	ds_write_b128 v245, v[140:143] offset:24576
	v_add_u32_e32 v245, s31, v194
	s_and_b64 vcc, exec, s[52:53]
	s_waitcnt vmcnt(0)
	ds_write_b128 v245, v[144:147] offset:24576
	s_cbranch_vccnz .LBB0_272
	v_add_co_u32_e32 v140, vcc, 0xc020000, v190
	s_nop 1
	v_addc_co_u32_e32 v141, vcc, 0, v191, vcc
	v_add_co_u32_e32 v144, vcc, 0x1eba4000, v188
	global_load_dwordx4 v[136:139], v[140:141], off offset:128
	s_nop 0
	global_load_dwordx4 v[140:143], v[140:141], off
	v_addc_co_u32_e32 v145, vcc, 0, v189, vcc
	global_load_dwordx4 v[144:147], v[144:145], off

.Lmla_exit_fix:
	v_mov_b64_e32 v[32:33], v[48:49]
	v_mov_b64_e32 v[34:35], v[50:51]
	v_mov_b64_e32 v[36:37], v[52:53]
	v_mov_b64_e32 v[38:39], v[54:55]
	v_mov_b64_e32 v[40:41], v[56:57]
	v_mov_b64_e32 v[42:43], v[58:59]
	v_mov_b64_e32 v[44:45], v[60:61]
	v_mov_b64_e32 v[46:47], v[62:63]
